# phase_ada K-loop: weight loads double-buffered two iterations ahead (8 loads in flight per lane instead of 2), loop unrolled by two; same FMAs in the same order
# baseline (speedup 1.0000x reference)
.LBB0_1731:
	s_or_b64 exec, exec, s[2:3]
	v_mov_b32_e32 v3, 0
	s_ashr_i32 s2, s17, 7
	v_mov_b32_e32 v2, v3
	v_mov_b32_e32 v1, v3
	v_mov_b32_e32 v0, v3
	v_mov_b32_e32 v11, v3
	v_mov_b32_e32 v10, v3
	v_mov_b32_e32 v9, v3
	v_mov_b32_e32 v8, v3
	v_mov_b32_e32 v15, v3
	v_mov_b32_e32 v14, v3
	v_mov_b32_e32 v13, v3
	v_mov_b32_e32 v12, v3
	v_mov_b32_e32 v21, v3
	v_mov_b32_e32 v20, v3
	v_mov_b32_e32 v19, v3
	v_mov_b32_e32 v18, v3
	v_mov_b32_e32 v7, v3
	v_mov_b32_e32 v6, v3
	v_mov_b32_e32 v5, v3
	v_mov_b32_e32 v4, v3
	v_mov_b32_e32 v41, v3
	v_mov_b32_e32 v40, v3
	v_mov_b32_e32 v39, v3
	v_mov_b32_e32 v38, v3
	v_mov_b32_e32 v45, v3
	v_mov_b32_e32 v44, v3
	v_mov_b32_e32 v43, v3
	v_mov_b32_e32 v42, v3
	v_mov_b32_e32 v49, v3
	v_mov_b32_e32 v48, v3
	v_mov_b32_e32 v47, v3
	v_mov_b32_e32 v46, v3
	v_mov_b32_e32 v25, v3
	v_mov_b32_e32 v24, v3
	v_mov_b32_e32 v23, v3
	v_mov_b32_e32 v22, v3
	v_mov_b32_e32 v57, v3
	v_mov_b32_e32 v56, v3
	v_mov_b32_e32 v55, v3
	v_mov_b32_e32 v54, v3
	s_waitcnt vmcnt(0)
	v_mov_b32_e32 v61, v3
	v_mov_b32_e32 v60, v3
	v_mov_b32_e32 v59, v3
	v_mov_b32_e32 v58, v3
	v_mov_b32_e32 v65, v3
	v_mov_b32_e32 v64, v3
	v_mov_b32_e32 v63, v3
	v_mov_b32_e32 v62, v3
	v_mov_b32_e32 v53, v3
	v_mov_b32_e32 v52, v3
	v_mov_b32_e32 v51, v3
	v_mov_b32_e32 v50, v3
	v_mov_b32_e32 v69, v3
	v_mov_b32_e32 v68, v3
	v_mov_b32_e32 v67, v3
	v_mov_b32_e32 v66, v3
	v_mov_b32_e32 v73, v3
	v_mov_b32_e32 v72, v3
	v_mov_b32_e32 v71, v3
	v_mov_b32_e32 v70, v3
	v_mov_b32_e32 v77, v3
	v_mov_b32_e32 v76, v3
	v_mov_b32_e32 v75, v3
	v_mov_b32_e32 v74, v3
	s_waitcnt lgkmcnt(0)
	s_barrier
	s_and_saveexec_b64 s[8:9], s[4:5]
	s_cbranch_execz .LBB0_1734
	s_and_b32 s0, s16, 0x7f
	s_mulk_i32 s0, 0x180
	s_mul_i32 s3, s2, 0x6000000
	s_mul_hi_i32 s1, s2, 0x6000000
	s_or_b32 s0, s3, s0
	v_mov_b32_e32 v74, 0
	v_lshl_add_u64 v[112:113], v[110:111], 0, s[0:1]
	s_mov_b64 s[10:11], 0
	v_mov_b32_e32 v149, v107
	v_mov_b32_e32 v75, v74
	v_mov_b32_e32 v76, v74
	v_mov_b32_e32 v77, v74
	v_mov_b32_e32 v70, v74
	v_mov_b32_e32 v71, v74
	v_mov_b32_e32 v72, v74
	v_mov_b32_e32 v73, v74
	v_mov_b32_e32 v66, v74
	v_mov_b32_e32 v67, v74
	v_mov_b32_e32 v68, v74
	v_mov_b32_e32 v69, v74
	v_mov_b32_e32 v50, v74
	v_mov_b32_e32 v51, v74
	v_mov_b32_e32 v52, v74
	v_mov_b32_e32 v53, v74
	v_mov_b32_e32 v62, v74
	v_mov_b32_e32 v63, v74
	v_mov_b32_e32 v64, v74
	v_mov_b32_e32 v65, v74
	v_mov_b32_e32 v58, v74
	v_mov_b32_e32 v59, v74
	v_mov_b32_e32 v60, v74
	v_mov_b32_e32 v61, v74
	v_mov_b32_e32 v54, v74
	v_mov_b32_e32 v55, v74
	v_mov_b32_e32 v56, v74
	v_mov_b32_e32 v57, v74
	v_mov_b32_e32 v22, v74
	v_mov_b32_e32 v23, v74
	v_mov_b32_e32 v24, v74
	v_mov_b32_e32 v25, v74
	v_mov_b32_e32 v46, v74
	v_mov_b32_e32 v47, v74
	v_mov_b32_e32 v48, v74
	v_mov_b32_e32 v49, v74
	v_mov_b32_e32 v42, v74
	v_mov_b32_e32 v43, v74
	v_mov_b32_e32 v44, v74
	v_mov_b32_e32 v45, v74
	v_mov_b32_e32 v38, v74
	v_mov_b32_e32 v39, v74
	v_mov_b32_e32 v40, v74
	v_mov_b32_e32 v41, v74
	v_mov_b32_e32 v4, v74
	v_mov_b32_e32 v5, v74
	v_mov_b32_e32 v6, v74
	v_mov_b32_e32 v7, v74
	v_mov_b32_e32 v18, v74
	v_mov_b32_e32 v19, v74
	v_mov_b32_e32 v20, v74
	v_mov_b32_e32 v21, v74
	v_mov_b32_e32 v12, v74
	v_mov_b32_e32 v13, v74
	v_mov_b32_e32 v14, v74
	v_mov_b32_e32 v15, v74
	v_mov_b32_e32 v8, v74
	v_mov_b32_e32 v9, v74
	v_mov_b32_e32 v10, v74
	v_mov_b32_e32 v11, v74
	v_mov_b32_e32 v0, v74
	v_mov_b32_e32 v1, v74
	v_mov_b32_e32 v2, v74
	v_mov_b32_e32 v3, v74
	s_mov_b32 s101, 0
	s_mov_b32 s100, 0xc000
	v_lshl_add_u64 v[192:193], v[112:113], 0, s[100:101]
	s_mov_b32 s100, 0x18000
	v_lshl_add_u64 v[194:195], v[112:113], 0, s[100:101]
	s_mov_b32 s100, 0x24000
	v_lshl_add_u64 v[196:197], v[112:113], 0, s[100:101]
	global_load_dwordx4 v[154:157], v[112:113], off
	global_load_dwordx4 v[158:161], v[192:193], off
	global_load_dwordx4 v[162:165], v[194:195], off
	global_load_dwordx4 v[166:169], v[196:197], off
	s_mov_b32 s100, 0x30000
	v_lshl_add_u64 v[198:199], v[112:113], 0, s[100:101]
	global_load_dwordx4 v[176:179], v[198:199], off
	v_lshl_add_u64 v[200:201], v[192:193], 0, s[100:101]
	global_load_dwordx4 v[180:183], v[200:201], off
	v_lshl_add_u64 v[202:203], v[194:195], 0, s[100:101]
	global_load_dwordx4 v[184:187], v[202:203], off
	v_lshl_add_u64 v[204:205], v[196:197], 0, s[100:101]
	global_load_dwordx4 v[188:191], v[204:205], off
.LBB0_1733:
	s_add_u32 s100, s10, 0x60000
	s_min_u32 s100, s100, 0x5d0000
	v_lshl_add_u64 v[114:115], v[112:113], 0, s[10:11]
	ds_read_b128 v[122:125], v149
	ds_read_b128 v[126:129], v149 offset:16
	ds_read_b128 v[102:105], v149 offset:32
	ds_read_b128 v[78:81], v149 offset:48
	ds_read_b128 v[98:101], v149 offset:64
	ds_read_b128 v[94:97], v149 offset:80
	ds_read_b128 v[90:93], v149 offset:96
	ds_read_b128 v[86:89], v149 offset:112
	ds_read_b128 v[26:29], v149 offset:128
	ds_read_b128 v[30:33], v149 offset:144
	ds_read_b128 v[34:37], v149 offset:160
	v_add_co_u32_e64 v82, s[0:1], s49, v114
	s_add_u32 s10, s10, 0x30000
	s_nop 0
	v_addc_co_u32_e64 v83, s[0:1], 0, v115, s[0:1]
	s_mov_b32 s0, 0x18000
	s_addc_u32 s11, s11, 0
	s_cmp_lg_u32 s10, 0x600000
	s_waitcnt vmcnt(7) lgkmcnt(10)
	v_pk_fma_f32 v[74:75], v[154:155], v[122:123], v[74:75] op_sel_hi:[1,0,1]
	v_pk_fma_f32 v[76:77], v[156:157], v[122:123], v[76:77] op_sel_hi:[1,0,1]
	v_pk_fma_f32 v[116:117], v[154:155], v[122:123], v[70:71] op_sel:[0,1,0]
	v_pk_fma_f32 v[118:119], v[156:157], v[122:123], v[72:73] op_sel:[0,1,0]
	v_pk_fma_f32 v[120:121], v[154:155], v[124:125], v[66:67] op_sel_hi:[1,0,1]
	v_pk_fma_f32 v[122:123], v[156:157], v[124:125], v[68:69] op_sel_hi:[1,0,1]
	s_waitcnt lgkmcnt(9)
	v_pk_fma_f32 v[66:67], v[154:155], v[128:129], v[54:55] op_sel_hi:[1,0,1]
	v_pk_fma_f32 v[68:69], v[156:157], v[128:129], v[56:57] op_sel_hi:[1,0,1]
	v_mov_b32_e32 v72, v129
	s_waitcnt lgkmcnt(8)
	v_pk_fma_f32 v[128:129], v[154:155], v[102:103], v[42:43] op_sel:[0,1,0]
	v_mov_b32_e32 v42, v105
	v_mov_b32_e32 v70, v125
	v_pk_fma_f32 v[62:63], v[154:155], v[126:127], v[62:63] op_sel_hi:[1,0,1]
	v_pk_fma_f32 v[64:65], v[156:157], v[126:127], v[64:65] op_sel_hi:[1,0,1]
	v_pk_fma_f32 v[58:59], v[154:155], v[126:127], v[58:59] op_sel:[0,1,0]
	v_pk_fma_f32 v[60:61], v[156:157], v[126:127], v[60:61] op_sel:[0,1,0]
	v_pk_fma_f32 v[124:125], v[154:155], v[102:103], v[46:47] op_sel_hi:[1,0,1]
	v_pk_fma_f32 v[126:127], v[156:157], v[102:103], v[48:49] op_sel_hi:[1,0,1]
	v_pk_fma_f32 v[130:131], v[156:157], v[102:103], v[44:45] op_sel:[0,1,0]
	v_pk_fma_f32 v[102:103], v[154:155], v[42:43], v[4:5] op_sel_hi:[1,0,1]
	v_add_co_u32_e64 v4, s[0:1], s0, v114
	v_pk_fma_f32 v[132:133], v[154:155], v[104:105], v[38:39] op_sel_hi:[1,0,1]
	s_nop 0
	v_addc_co_u32_e64 v5, s[0:1], 0, v115, s[0:1]
	s_mov_b32 s0, 0x24000
	s_nop 0
	v_add_co_u32_e64 v114, s[0:1], s0, v114
	v_pk_fma_f32 v[134:135], v[156:157], v[104:105], v[40:41] op_sel_hi:[1,0,1]
	v_pk_fma_f32 v[104:105], v[156:157], v[42:43], v[6:7] op_sel_hi:[1,0,1]
	v_addc_co_u32_e64 v115, s[0:1], 0, v115, s[0:1]
	s_waitcnt vmcnt(6) lgkmcnt(6)
	v_pk_fma_f32 v[42:43], v[158:159], v[100:101], v[120:121] op_sel_hi:[1,0,1]
	s_waitcnt lgkmcnt(5)
	v_pk_fma_f32 v[46:47], v[158:159], v[94:95], v[62:63] op_sel_hi:[1,0,1]
	v_pk_fma_f32 v[48:49], v[160:161], v[94:95], v[64:65] op_sel_hi:[1,0,1]
	v_pk_fma_f32 v[58:59], v[158:159], v[94:95], v[58:59] op_sel:[0,1,0]
	v_pk_fma_f32 v[60:61], v[160:161], v[94:95], v[60:61] op_sel:[0,1,0]
	v_pk_fma_f32 v[62:63], v[158:159], v[96:97], v[66:67] op_sel_hi:[1,0,1]
	v_pk_fma_f32 v[64:65], v[160:161], v[96:97], v[68:69] op_sel_hi:[1,0,1]
	v_mov_b32_e32 v120, v97
	ds_read_b128 v[54:57], v149 offset:176
	ds_read_b128 v[38:41], v149 offset:192
	v_pk_fma_f32 v[140:141], v[154:155], v[78:79], v[12:13] op_sel:[0,1,0]
	v_mov_b32_e32 v12, v81
	v_pk_fma_f32 v[50:51], v[154:155], v[70:71], v[50:51] op_sel_hi:[1,0,1]
	v_pk_fma_f32 v[52:53], v[156:157], v[70:71], v[52:53] op_sel_hi:[1,0,1]
	v_pk_fma_f32 v[22:23], v[154:155], v[72:73], v[22:23] op_sel_hi:[1,0,1]
	v_pk_fma_f32 v[24:25], v[156:157], v[72:73], v[24:25] op_sel_hi:[1,0,1]
	v_pk_fma_f32 v[136:137], v[154:155], v[78:79], v[18:19] op_sel_hi:[1,0,1]
	v_pk_fma_f32 v[138:139], v[156:157], v[78:79], v[20:21] op_sel_hi:[1,0,1]
	v_pk_fma_f32 v[142:143], v[156:157], v[78:79], v[14:15] op_sel:[0,1,0]
	v_pk_fma_f32 v[144:145], v[154:155], v[80:81], v[8:9] op_sel_hi:[1,0,1]
	v_pk_fma_f32 v[146:147], v[156:157], v[80:81], v[10:11] op_sel_hi:[1,0,1]
	ds_read_b128 v[8:11], v149 offset:208
	v_pk_fma_f32 v[70:71], v[154:155], v[12:13], v[0:1] op_sel_hi:[1,0,1]
	v_pk_fma_f32 v[72:73], v[156:157], v[12:13], v[2:3] op_sel_hi:[1,0,1]
	ds_read_b128 v[0:3], v149 offset:224
	ds_read_b128 v[78:81], v149 offset:240
	v_pk_fma_f32 v[20:21], v[160:161], v[98:99], v[118:119] op_sel:[0,1,0]
	v_pk_fma_f32 v[44:45], v[160:161], v[100:101], v[122:123] op_sel_hi:[1,0,1]
	v_mov_b32_e32 v118, v101
	s_waitcnt lgkmcnt(9)
	v_pk_fma_f32 v[66:67], v[158:159], v[90:91], v[124:125] op_sel_hi:[1,0,1]
	v_mov_b32_e32 v122, v93
	s_waitcnt lgkmcnt(8)
	v_mov_b32_e32 v124, v89
	v_pk_fma_f32 v[12:13], v[158:159], v[98:99], v[74:75] op_sel_hi:[1,0,1]
	v_pk_fma_f32 v[14:15], v[160:161], v[98:99], v[76:77] op_sel_hi:[1,0,1]
	v_pk_fma_f32 v[18:19], v[158:159], v[98:99], v[116:117] op_sel:[0,1,0]
	v_pk_fma_f32 v[68:69], v[160:161], v[90:91], v[126:127] op_sel_hi:[1,0,1]
	v_pk_fma_f32 v[74:75], v[158:159], v[90:91], v[128:129] op_sel:[0,1,0]
	v_pk_fma_f32 v[76:77], v[160:161], v[90:91], v[130:131] op_sel:[0,1,0]
	v_pk_fma_f32 v[90:91], v[158:159], v[92:93], v[132:133] op_sel_hi:[1,0,1]
	v_pk_fma_f32 v[98:99], v[160:161], v[92:93], v[134:135] op_sel_hi:[1,0,1]
	v_pk_fma_f32 v[92:93], v[158:159], v[86:87], v[136:137] op_sel_hi:[1,0,1]
	v_pk_fma_f32 v[100:101], v[160:161], v[86:87], v[138:139] op_sel_hi:[1,0,1]
	v_pk_fma_f32 v[114:115], v[158:159], v[86:87], v[140:141] op_sel:[0,1,0]
	v_pk_fma_f32 v[86:87], v[160:161], v[86:87], v[142:143] op_sel:[0,1,0]
	v_pk_fma_f32 v[116:117], v[158:159], v[88:89], v[144:145] op_sel_hi:[1,0,1]
	v_pk_fma_f32 v[88:89], v[160:161], v[88:89], v[146:147] op_sel_hi:[1,0,1]
	s_waitcnt lgkmcnt(7)
	v_mov_b32_e32 v126, v29
	s_waitcnt lgkmcnt(6)
	v_mov_b32_e32 v128, v33
	v_pk_fma_f32 v[50:51], v[158:159], v[118:119], v[50:51] op_sel_hi:[1,0,1]
	v_pk_fma_f32 v[52:53], v[160:161], v[118:119], v[52:53] op_sel_hi:[1,0,1]
	s_waitcnt lgkmcnt(5)
	v_mov_b32_e32 v118, v37
	v_pk_fma_f32 v[22:23], v[158:159], v[120:121], v[22:23] op_sel_hi:[1,0,1]
	v_pk_fma_f32 v[24:25], v[160:161], v[120:121], v[24:25] op_sel_hi:[1,0,1]
	s_waitcnt lgkmcnt(4)
	v_mov_b32_e32 v120, v57
	v_pk_fma_f32 v[102:103], v[158:159], v[122:123], v[102:103] op_sel_hi:[1,0,1]
	v_pk_fma_f32 v[104:105], v[160:161], v[122:123], v[104:105] op_sel_hi:[1,0,1]
	v_pk_fma_f32 v[70:71], v[158:159], v[124:125], v[70:71] op_sel_hi:[1,0,1]
	v_pk_fma_f32 v[72:73], v[160:161], v[124:125], v[72:73] op_sel_hi:[1,0,1]
	s_waitcnt lgkmcnt(3)
	v_mov_b32_e32 v122, v41
	s_waitcnt lgkmcnt(2)
	v_mov_b32_e32 v82, v11
	s_waitcnt lgkmcnt(1)
	v_mov_b32_e32 v84, v3
	s_waitcnt lgkmcnt(0)
	v_mov_b32_e32 v124, v81
	v_add_u32_e32 v149, 0x100, v149
	v_lshl_add_u64 v[198:199], v[112:113], 0, s[100:101]
	global_load_dwordx4 v[154:157], v[198:199], off
	s_waitcnt vmcnt(6)
	v_pk_fma_f32 v[12:13], v[162:163], v[26:27], v[12:13] op_sel_hi:[1,0,1]
	v_pk_fma_f32 v[14:15], v[164:165], v[26:27], v[14:15] op_sel_hi:[1,0,1]
	v_pk_fma_f32 v[18:19], v[162:163], v[26:27], v[18:19] op_sel:[0,1,0]
	v_pk_fma_f32 v[20:21], v[164:165], v[26:27], v[20:21] op_sel:[0,1,0]
	v_pk_fma_f32 v[26:27], v[162:163], v[28:29], v[42:43] op_sel_hi:[1,0,1]
	v_pk_fma_f32 v[28:29], v[164:165], v[28:29], v[44:45] op_sel_hi:[1,0,1]
	v_pk_fma_f32 v[42:43], v[162:163], v[126:127], v[50:51] op_sel_hi:[1,0,1]
	v_pk_fma_f32 v[44:45], v[164:165], v[126:127], v[52:53] op_sel_hi:[1,0,1]
	v_pk_fma_f32 v[46:47], v[162:163], v[30:31], v[46:47] op_sel_hi:[1,0,1]
	v_pk_fma_f32 v[48:49], v[164:165], v[30:31], v[48:49] op_sel_hi:[1,0,1]
	v_pk_fma_f32 v[58:59], v[162:163], v[30:31], v[58:59] op_sel:[0,1,0]
	v_pk_fma_f32 v[30:31], v[164:165], v[30:31], v[60:61] op_sel:[0,1,0]
	v_pk_fma_f32 v[126:127], v[162:163], v[32:33], v[62:63] op_sel_hi:[1,0,1]
	v_pk_fma_f32 v[32:33], v[164:165], v[32:33], v[64:65] op_sel_hi:[1,0,1]
	v_pk_fma_f32 v[22:23], v[162:163], v[128:129], v[22:23] op_sel_hi:[1,0,1]
	v_pk_fma_f32 v[24:25], v[164:165], v[128:129], v[24:25] op_sel_hi:[1,0,1]
	v_pk_fma_f32 v[128:129], v[162:163], v[34:35], v[66:67] op_sel_hi:[1,0,1]
	v_pk_fma_f32 v[130:131], v[164:165], v[34:35], v[68:69] op_sel_hi:[1,0,1]
	v_pk_fma_f32 v[132:133], v[162:163], v[34:35], v[74:75] op_sel:[0,1,0]
	v_pk_fma_f32 v[34:35], v[164:165], v[34:35], v[76:77] op_sel:[0,1,0]
	v_pk_fma_f32 v[90:91], v[162:163], v[36:37], v[90:91] op_sel_hi:[1,0,1]
	v_pk_fma_f32 v[36:37], v[164:165], v[36:37], v[98:99] op_sel_hi:[1,0,1]
	v_pk_fma_f32 v[98:99], v[162:163], v[118:119], v[102:103] op_sel_hi:[1,0,1]
	v_pk_fma_f32 v[102:103], v[164:165], v[118:119], v[104:105] op_sel_hi:[1,0,1]
	v_pk_fma_f32 v[92:93], v[162:163], v[54:55], v[92:93] op_sel_hi:[1,0,1]
	v_pk_fma_f32 v[100:101], v[164:165], v[54:55], v[100:101] op_sel_hi:[1,0,1]
	v_pk_fma_f32 v[104:105], v[162:163], v[54:55], v[114:115] op_sel:[0,1,0]
	v_pk_fma_f32 v[86:87], v[164:165], v[54:55], v[86:87] op_sel:[0,1,0]
	v_pk_fma_f32 v[114:115], v[162:163], v[56:57], v[116:117] op_sel_hi:[1,0,1]
	v_pk_fma_f32 v[88:89], v[164:165], v[56:57], v[88:89] op_sel_hi:[1,0,1]
	v_pk_fma_f32 v[116:117], v[162:163], v[120:121], v[70:71] op_sel_hi:[1,0,1]
	v_pk_fma_f32 v[118:119], v[164:165], v[120:121], v[72:73] op_sel_hi:[1,0,1]
	v_lshl_add_u64 v[200:201], v[192:193], 0, s[100:101]
	global_load_dwordx4 v[158:161], v[200:201], off
	s_waitcnt vmcnt(6)
	v_pk_fma_f32 v[74:75], v[166:167], v[38:39], v[12:13] op_sel_hi:[1,0,1]
	v_pk_fma_f32 v[76:77], v[168:169], v[38:39], v[14:15] op_sel_hi:[1,0,1]
	v_pk_fma_f32 v[70:71], v[166:167], v[38:39], v[18:19] op_sel:[0,1,0]
	v_pk_fma_f32 v[72:73], v[168:169], v[38:39], v[20:21] op_sel:[0,1,0]
	v_pk_fma_f32 v[66:67], v[166:167], v[40:41], v[26:27] op_sel_hi:[1,0,1]
	v_pk_fma_f32 v[68:69], v[168:169], v[40:41], v[28:29] op_sel_hi:[1,0,1]
	v_pk_fma_f32 v[50:51], v[166:167], v[122:123], v[42:43] op_sel_hi:[1,0,1]
	v_pk_fma_f32 v[52:53], v[168:169], v[122:123], v[44:45] op_sel_hi:[1,0,1]
	v_pk_fma_f32 v[62:63], v[166:167], v[8:9], v[46:47] op_sel_hi:[1,0,1]
	v_pk_fma_f32 v[64:65], v[168:169], v[8:9], v[48:49] op_sel_hi:[1,0,1]
	v_pk_fma_f32 v[58:59], v[166:167], v[8:9], v[58:59] op_sel:[0,1,0]
	v_pk_fma_f32 v[60:61], v[168:169], v[8:9], v[30:31] op_sel:[0,1,0]
	v_pk_fma_f32 v[54:55], v[166:167], v[10:11], v[126:127] op_sel_hi:[1,0,1]
	v_pk_fma_f32 v[56:57], v[168:169], v[10:11], v[32:33] op_sel_hi:[1,0,1]
	v_pk_fma_f32 v[22:23], v[166:167], v[82:83], v[22:23] op_sel_hi:[1,0,1]
	v_pk_fma_f32 v[24:25], v[168:169], v[82:83], v[24:25] op_sel_hi:[1,0,1]
	v_pk_fma_f32 v[46:47], v[166:167], v[0:1], v[128:129] op_sel_hi:[1,0,1]
	v_pk_fma_f32 v[48:49], v[168:169], v[0:1], v[130:131] op_sel_hi:[1,0,1]
	v_pk_fma_f32 v[42:43], v[166:167], v[0:1], v[132:133] op_sel:[0,1,0]
	v_pk_fma_f32 v[44:45], v[168:169], v[0:1], v[34:35] op_sel:[0,1,0]
	v_pk_fma_f32 v[38:39], v[166:167], v[2:3], v[90:91] op_sel_hi:[1,0,1]
	v_pk_fma_f32 v[40:41], v[168:169], v[2:3], v[36:37] op_sel_hi:[1,0,1]
	v_pk_fma_f32 v[4:5], v[166:167], v[84:85], v[98:99] op_sel_hi:[1,0,1]
	v_pk_fma_f32 v[6:7], v[168:169], v[84:85], v[102:103] op_sel_hi:[1,0,1]
	v_pk_fma_f32 v[18:19], v[166:167], v[78:79], v[92:93] op_sel_hi:[1,0,1]
	v_pk_fma_f32 v[20:21], v[168:169], v[78:79], v[100:101] op_sel_hi:[1,0,1]
	v_pk_fma_f32 v[12:13], v[166:167], v[78:79], v[104:105] op_sel:[0,1,0]
	v_pk_fma_f32 v[14:15], v[168:169], v[78:79], v[86:87] op_sel:[0,1,0]
	v_pk_fma_f32 v[8:9], v[166:167], v[80:81], v[114:115] op_sel_hi:[1,0,1]
	v_pk_fma_f32 v[10:11], v[168:169], v[80:81], v[88:89] op_sel_hi:[1,0,1]
	v_pk_fma_f32 v[0:1], v[166:167], v[124:125], v[116:117] op_sel_hi:[1,0,1]
	v_pk_fma_f32 v[2:3], v[168:169], v[124:125], v[118:119] op_sel_hi:[1,0,1]
	v_lshl_add_u64 v[202:203], v[194:195], 0, s[100:101]
	global_load_dwordx4 v[162:165], v[202:203], off
	v_lshl_add_u64 v[204:205], v[196:197], 0, s[100:101]
	global_load_dwordx4 v[166:169], v[204:205], off
	s_add_u32 s100, s10, 0x60000
	s_min_u32 s100, s100, 0x5d0000
	v_lshl_add_u64 v[114:115], v[112:113], 0, s[10:11]
	ds_read_b128 v[122:125], v149
	ds_read_b128 v[126:129], v149 offset:16
	ds_read_b128 v[102:105], v149 offset:32
	ds_read_b128 v[78:81], v149 offset:48
	ds_read_b128 v[98:101], v149 offset:64
	ds_read_b128 v[94:97], v149 offset:80
	ds_read_b128 v[90:93], v149 offset:96
	ds_read_b128 v[86:89], v149 offset:112
	ds_read_b128 v[26:29], v149 offset:128
	ds_read_b128 v[30:33], v149 offset:144
	ds_read_b128 v[34:37], v149 offset:160
	v_add_co_u32_e64 v82, s[0:1], s49, v114
	s_add_u32 s10, s10, 0x30000
	s_nop 0
	v_addc_co_u32_e64 v83, s[0:1], 0, v115, s[0:1]
	s_mov_b32 s0, 0x18000
	s_addc_u32 s11, s11, 0
	s_cmp_lg_u32 s10, 0x600000
	s_waitcnt vmcnt(7) lgkmcnt(10)
	v_pk_fma_f32 v[74:75], v[176:177], v[122:123], v[74:75] op_sel_hi:[1,0,1]
	v_pk_fma_f32 v[76:77], v[178:179], v[122:123], v[76:77] op_sel_hi:[1,0,1]
	v_pk_fma_f32 v[116:117], v[176:177], v[122:123], v[70:71] op_sel:[0,1,0]
	v_pk_fma_f32 v[118:119], v[178:179], v[122:123], v[72:73] op_sel:[0,1,0]
	v_pk_fma_f32 v[120:121], v[176:177], v[124:125], v[66:67] op_sel_hi:[1,0,1]
	v_pk_fma_f32 v[122:123], v[178:179], v[124:125], v[68:69] op_sel_hi:[1,0,1]
	s_waitcnt lgkmcnt(9)
	v_pk_fma_f32 v[66:67], v[176:177], v[128:129], v[54:55] op_sel_hi:[1,0,1]
	v_pk_fma_f32 v[68:69], v[178:179], v[128:129], v[56:57] op_sel_hi:[1,0,1]
	v_mov_b32_e32 v72, v129
	s_waitcnt lgkmcnt(8)
	v_pk_fma_f32 v[128:129], v[176:177], v[102:103], v[42:43] op_sel:[0,1,0]
	v_mov_b32_e32 v42, v105
	v_mov_b32_e32 v70, v125
	v_pk_fma_f32 v[62:63], v[176:177], v[126:127], v[62:63] op_sel_hi:[1,0,1]
	v_pk_fma_f32 v[64:65], v[178:179], v[126:127], v[64:65] op_sel_hi:[1,0,1]
	v_pk_fma_f32 v[58:59], v[176:177], v[126:127], v[58:59] op_sel:[0,1,0]
	v_pk_fma_f32 v[60:61], v[178:179], v[126:127], v[60:61] op_sel:[0,1,0]
	v_pk_fma_f32 v[124:125], v[176:177], v[102:103], v[46:47] op_sel_hi:[1,0,1]
	v_pk_fma_f32 v[126:127], v[178:179], v[102:103], v[48:49] op_sel_hi:[1,0,1]
	v_pk_fma_f32 v[130:131], v[178:179], v[102:103], v[44:45] op_sel:[0,1,0]
	v_pk_fma_f32 v[102:103], v[176:177], v[42:43], v[4:5] op_sel_hi:[1,0,1]
	v_add_co_u32_e64 v4, s[0:1], s0, v114
	v_pk_fma_f32 v[132:133], v[176:177], v[104:105], v[38:39] op_sel_hi:[1,0,1]
	s_nop 0
	v_addc_co_u32_e64 v5, s[0:1], 0, v115, s[0:1]
	s_mov_b32 s0, 0x24000
	s_nop 0
	v_add_co_u32_e64 v114, s[0:1], s0, v114
	v_pk_fma_f32 v[134:135], v[178:179], v[104:105], v[40:41] op_sel_hi:[1,0,1]
	v_pk_fma_f32 v[104:105], v[178:179], v[42:43], v[6:7] op_sel_hi:[1,0,1]
	v_addc_co_u32_e64 v115, s[0:1], 0, v115, s[0:1]
	s_waitcnt vmcnt(6) lgkmcnt(6)
	v_pk_fma_f32 v[42:43], v[180:181], v[100:101], v[120:121] op_sel_hi:[1,0,1]
	s_waitcnt lgkmcnt(5)
	v_pk_fma_f32 v[46:47], v[180:181], v[94:95], v[62:63] op_sel_hi:[1,0,1]
	v_pk_fma_f32 v[48:49], v[182:183], v[94:95], v[64:65] op_sel_hi:[1,0,1]
	v_pk_fma_f32 v[58:59], v[180:181], v[94:95], v[58:59] op_sel:[0,1,0]
	v_pk_fma_f32 v[60:61], v[182:183], v[94:95], v[60:61] op_sel:[0,1,0]
	v_pk_fma_f32 v[62:63], v[180:181], v[96:97], v[66:67] op_sel_hi:[1,0,1]
	v_pk_fma_f32 v[64:65], v[182:183], v[96:97], v[68:69] op_sel_hi:[1,0,1]
	v_mov_b32_e32 v120, v97
	ds_read_b128 v[54:57], v149 offset:176
	ds_read_b128 v[38:41], v149 offset:192
	v_pk_fma_f32 v[140:141], v[176:177], v[78:79], v[12:13] op_sel:[0,1,0]
	v_mov_b32_e32 v12, v81
	v_pk_fma_f32 v[50:51], v[176:177], v[70:71], v[50:51] op_sel_hi:[1,0,1]
	v_pk_fma_f32 v[52:53], v[178:179], v[70:71], v[52:53] op_sel_hi:[1,0,1]
	v_pk_fma_f32 v[22:23], v[176:177], v[72:73], v[22:23] op_sel_hi:[1,0,1]
	v_pk_fma_f32 v[24:25], v[178:179], v[72:73], v[24:25] op_sel_hi:[1,0,1]
	v_pk_fma_f32 v[136:137], v[176:177], v[78:79], v[18:19] op_sel_hi:[1,0,1]
	v_pk_fma_f32 v[138:139], v[178:179], v[78:79], v[20:21] op_sel_hi:[1,0,1]
	v_pk_fma_f32 v[142:143], v[178:179], v[78:79], v[14:15] op_sel:[0,1,0]
	v_pk_fma_f32 v[144:145], v[176:177], v[80:81], v[8:9] op_sel_hi:[1,0,1]
	v_pk_fma_f32 v[146:147], v[178:179], v[80:81], v[10:11] op_sel_hi:[1,0,1]
	ds_read_b128 v[8:11], v149 offset:208
	v_pk_fma_f32 v[70:71], v[176:177], v[12:13], v[0:1] op_sel_hi:[1,0,1]
	v_pk_fma_f32 v[72:73], v[178:179], v[12:13], v[2:3] op_sel_hi:[1,0,1]
	ds_read_b128 v[0:3], v149 offset:224
	ds_read_b128 v[78:81], v149 offset:240
	v_pk_fma_f32 v[20:21], v[182:183], v[98:99], v[118:119] op_sel:[0,1,0]
	v_pk_fma_f32 v[44:45], v[182:183], v[100:101], v[122:123] op_sel_hi:[1,0,1]
	v_mov_b32_e32 v118, v101
	s_waitcnt lgkmcnt(9)
	v_pk_fma_f32 v[66:67], v[180:181], v[90:91], v[124:125] op_sel_hi:[1,0,1]
	v_mov_b32_e32 v122, v93
	s_waitcnt lgkmcnt(8)
	v_mov_b32_e32 v124, v89
	v_pk_fma_f32 v[12:13], v[180:181], v[98:99], v[74:75] op_sel_hi:[1,0,1]
	v_pk_fma_f32 v[14:15], v[182:183], v[98:99], v[76:77] op_sel_hi:[1,0,1]
	v_pk_fma_f32 v[18:19], v[180:181], v[98:99], v[116:117] op_sel:[0,1,0]
	v_pk_fma_f32 v[68:69], v[182:183], v[90:91], v[126:127] op_sel_hi:[1,0,1]
	v_pk_fma_f32 v[74:75], v[180:181], v[90:91], v[128:129] op_sel:[0,1,0]
	v_pk_fma_f32 v[76:77], v[182:183], v[90:91], v[130:131] op_sel:[0,1,0]
	v_pk_fma_f32 v[90:91], v[180:181], v[92:93], v[132:133] op_sel_hi:[1,0,1]
	v_pk_fma_f32 v[98:99], v[182:183], v[92:93], v[134:135] op_sel_hi:[1,0,1]
	v_pk_fma_f32 v[92:93], v[180:181], v[86:87], v[136:137] op_sel_hi:[1,0,1]
	v_pk_fma_f32 v[100:101], v[182:183], v[86:87], v[138:139] op_sel_hi:[1,0,1]
	v_pk_fma_f32 v[114:115], v[180:181], v[86:87], v[140:141] op_sel:[0,1,0]
	v_pk_fma_f32 v[86:87], v[182:183], v[86:87], v[142:143] op_sel:[0,1,0]
	v_pk_fma_f32 v[116:117], v[180:181], v[88:89], v[144:145] op_sel_hi:[1,0,1]
	v_pk_fma_f32 v[88:89], v[182:183], v[88:89], v[146:147] op_sel_hi:[1,0,1]
	s_waitcnt lgkmcnt(7)
	v_mov_b32_e32 v126, v29
	s_waitcnt lgkmcnt(6)
	v_mov_b32_e32 v128, v33
	v_pk_fma_f32 v[50:51], v[180:181], v[118:119], v[50:51] op_sel_hi:[1,0,1]
	v_pk_fma_f32 v[52:53], v[182:183], v[118:119], v[52:53] op_sel_hi:[1,0,1]
	s_waitcnt lgkmcnt(5)
	v_mov_b32_e32 v118, v37
	v_pk_fma_f32 v[22:23], v[180:181], v[120:121], v[22:23] op_sel_hi:[1,0,1]
	v_pk_fma_f32 v[24:25], v[182:183], v[120:121], v[24:25] op_sel_hi:[1,0,1]
	s_waitcnt lgkmcnt(4)
	v_mov_b32_e32 v120, v57
	v_pk_fma_f32 v[102:103], v[180:181], v[122:123], v[102:103] op_sel_hi:[1,0,1]
	v_pk_fma_f32 v[104:105], v[182:183], v[122:123], v[104:105] op_sel_hi:[1,0,1]
	v_pk_fma_f32 v[70:71], v[180:181], v[124:125], v[70:71] op_sel_hi:[1,0,1]
	v_pk_fma_f32 v[72:73], v[182:183], v[124:125], v[72:73] op_sel_hi:[1,0,1]
	s_waitcnt lgkmcnt(3)
	v_mov_b32_e32 v122, v41
	s_waitcnt lgkmcnt(2)
	v_mov_b32_e32 v82, v11
	s_waitcnt lgkmcnt(1)
	v_mov_b32_e32 v84, v3
	s_waitcnt lgkmcnt(0)
	v_mov_b32_e32 v124, v81
	v_add_u32_e32 v149, 0x100, v149
	v_lshl_add_u64 v[198:199], v[112:113], 0, s[100:101]
	global_load_dwordx4 v[176:179], v[198:199], off
	s_waitcnt vmcnt(6)
	v_pk_fma_f32 v[12:13], v[184:185], v[26:27], v[12:13] op_sel_hi:[1,0,1]
	v_pk_fma_f32 v[14:15], v[186:187], v[26:27], v[14:15] op_sel_hi:[1,0,1]
	v_pk_fma_f32 v[18:19], v[184:185], v[26:27], v[18:19] op_sel:[0,1,0]
	v_pk_fma_f32 v[20:21], v[186:187], v[26:27], v[20:21] op_sel:[0,1,0]
	v_pk_fma_f32 v[26:27], v[184:185], v[28:29], v[42:43] op_sel_hi:[1,0,1]
	v_pk_fma_f32 v[28:29], v[186:187], v[28:29], v[44:45] op_sel_hi:[1,0,1]
	v_pk_fma_f32 v[42:43], v[184:185], v[126:127], v[50:51] op_sel_hi:[1,0,1]
	v_pk_fma_f32 v[44:45], v[186:187], v[126:127], v[52:53] op_sel_hi:[1,0,1]
	v_pk_fma_f32 v[46:47], v[184:185], v[30:31], v[46:47] op_sel_hi:[1,0,1]
	v_pk_fma_f32 v[48:49], v[186:187], v[30:31], v[48:49] op_sel_hi:[1,0,1]
	v_pk_fma_f32 v[58:59], v[184:185], v[30:31], v[58:59] op_sel:[0,1,0]
	v_pk_fma_f32 v[30:31], v[186:187], v[30:31], v[60:61] op_sel:[0,1,0]
	v_pk_fma_f32 v[126:127], v[184:185], v[32:33], v[62:63] op_sel_hi:[1,0,1]
	v_pk_fma_f32 v[32:33], v[186:187], v[32:33], v[64:65] op_sel_hi:[1,0,1]
	v_pk_fma_f32 v[22:23], v[184:185], v[128:129], v[22:23] op_sel_hi:[1,0,1]
	v_pk_fma_f32 v[24:25], v[186:187], v[128:129], v[24:25] op_sel_hi:[1,0,1]
	v_pk_fma_f32 v[128:129], v[184:185], v[34:35], v[66:67] op_sel_hi:[1,0,1]
	v_pk_fma_f32 v[130:131], v[186:187], v[34:35], v[68:69] op_sel_hi:[1,0,1]
	v_pk_fma_f32 v[132:133], v[184:185], v[34:35], v[74:75] op_sel:[0,1,0]
	v_pk_fma_f32 v[34:35], v[186:187], v[34:35], v[76:77] op_sel:[0,1,0]
	v_pk_fma_f32 v[90:91], v[184:185], v[36:37], v[90:91] op_sel_hi:[1,0,1]
	v_pk_fma_f32 v[36:37], v[186:187], v[36:37], v[98:99] op_sel_hi:[1,0,1]
	v_pk_fma_f32 v[98:99], v[184:185], v[118:119], v[102:103] op_sel_hi:[1,0,1]
	v_pk_fma_f32 v[102:103], v[186:187], v[118:119], v[104:105] op_sel_hi:[1,0,1]
	v_pk_fma_f32 v[92:93], v[184:185], v[54:55], v[92:93] op_sel_hi:[1,0,1]
	v_pk_fma_f32 v[100:101], v[186:187], v[54:55], v[100:101] op_sel_hi:[1,0,1]
	v_pk_fma_f32 v[104:105], v[184:185], v[54:55], v[114:115] op_sel:[0,1,0]
	v_pk_fma_f32 v[86:87], v[186:187], v[54:55], v[86:87] op_sel:[0,1,0]
	v_pk_fma_f32 v[114:115], v[184:185], v[56:57], v[116:117] op_sel_hi:[1,0,1]
	v_pk_fma_f32 v[88:89], v[186:187], v[56:57], v[88:89] op_sel_hi:[1,0,1]
	v_pk_fma_f32 v[116:117], v[184:185], v[120:121], v[70:71] op_sel_hi:[1,0,1]
	v_pk_fma_f32 v[118:119], v[186:187], v[120:121], v[72:73] op_sel_hi:[1,0,1]
	v_lshl_add_u64 v[200:201], v[192:193], 0, s[100:101]
	global_load_dwordx4 v[180:183], v[200:201], off
	s_waitcnt vmcnt(6)
	v_pk_fma_f32 v[74:75], v[188:189], v[38:39], v[12:13] op_sel_hi:[1,0,1]
	v_pk_fma_f32 v[76:77], v[190:191], v[38:39], v[14:15] op_sel_hi:[1,0,1]
	v_pk_fma_f32 v[70:71], v[188:189], v[38:39], v[18:19] op_sel:[0,1,0]
	v_pk_fma_f32 v[72:73], v[190:191], v[38:39], v[20:21] op_sel:[0,1,0]
	v_pk_fma_f32 v[66:67], v[188:189], v[40:41], v[26:27] op_sel_hi:[1,0,1]
	v_pk_fma_f32 v[68:69], v[190:191], v[40:41], v[28:29] op_sel_hi:[1,0,1]
	v_pk_fma_f32 v[50:51], v[188:189], v[122:123], v[42:43] op_sel_hi:[1,0,1]
	v_pk_fma_f32 v[52:53], v[190:191], v[122:123], v[44:45] op_sel_hi:[1,0,1]
	v_pk_fma_f32 v[62:63], v[188:189], v[8:9], v[46:47] op_sel_hi:[1,0,1]
	v_pk_fma_f32 v[64:65], v[190:191], v[8:9], v[48:49] op_sel_hi:[1,0,1]
	v_pk_fma_f32 v[58:59], v[188:189], v[8:9], v[58:59] op_sel:[0,1,0]
	v_pk_fma_f32 v[60:61], v[190:191], v[8:9], v[30:31] op_sel:[0,1,0]
	v_pk_fma_f32 v[54:55], v[188:189], v[10:11], v[126:127] op_sel_hi:[1,0,1]
	v_pk_fma_f32 v[56:57], v[190:191], v[10:11], v[32:33] op_sel_hi:[1,0,1]
	v_pk_fma_f32 v[22:23], v[188:189], v[82:83], v[22:23] op_sel_hi:[1,0,1]
	v_pk_fma_f32 v[24:25], v[190:191], v[82:83], v[24:25] op_sel_hi:[1,0,1]
	v_pk_fma_f32 v[46:47], v[188:189], v[0:1], v[128:129] op_sel_hi:[1,0,1]
	v_pk_fma_f32 v[48:49], v[190:191], v[0:1], v[130:131] op_sel_hi:[1,0,1]
	v_pk_fma_f32 v[42:43], v[188:189], v[0:1], v[132:133] op_sel:[0,1,0]
	v_pk_fma_f32 v[44:45], v[190:191], v[0:1], v[34:35] op_sel:[0,1,0]
	v_pk_fma_f32 v[38:39], v[188:189], v[2:3], v[90:91] op_sel_hi:[1,0,1]
	v_pk_fma_f32 v[40:41], v[190:191], v[2:3], v[36:37] op_sel_hi:[1,0,1]
	v_pk_fma_f32 v[4:5], v[188:189], v[84:85], v[98:99] op_sel_hi:[1,0,1]
	v_pk_fma_f32 v[6:7], v[190:191], v[84:85], v[102:103] op_sel_hi:[1,0,1]
	v_pk_fma_f32 v[18:19], v[188:189], v[78:79], v[92:93] op_sel_hi:[1,0,1]
	v_pk_fma_f32 v[20:21], v[190:191], v[78:79], v[100:101] op_sel_hi:[1,0,1]
	v_pk_fma_f32 v[12:13], v[188:189], v[78:79], v[104:105] op_sel:[0,1,0]
	v_pk_fma_f32 v[14:15], v[190:191], v[78:79], v[86:87] op_sel:[0,1,0]
	v_pk_fma_f32 v[8:9], v[188:189], v[80:81], v[114:115] op_sel_hi:[1,0,1]
	v_pk_fma_f32 v[10:11], v[190:191], v[80:81], v[88:89] op_sel_hi:[1,0,1]
	v_pk_fma_f32 v[0:1], v[188:189], v[124:125], v[116:117] op_sel_hi:[1,0,1]
	v_pk_fma_f32 v[2:3], v[190:191], v[124:125], v[118:119] op_sel_hi:[1,0,1]
	v_lshl_add_u64 v[202:203], v[194:195], 0, s[100:101]
	global_load_dwordx4 v[184:187], v[202:203], off
	v_lshl_add_u64 v[204:205], v[196:197], 0, s[100:101]
	global_load_dwordx4 v[188:191], v[204:205], off
	s_cbranch_scc1 .LBB0_1733
	s_waitcnt vmcnt(0)
